# weight-conversion item loops rewritten (all loads of an item in flight, scalar dispatch) at P0 and seams 0,2,3,5; P8 output stores without nt
# speedup vs baseline: 1.0059x; 1.0059x over previous
.LBB0_19:
	s_cmp_lt_i32 s86, 1
	s_cselect_b64 s[2:3], -1, 0
	s_cmp_gt_i32 s87, 0
	s_cselect_b64 s[4:5], -1, 0
	s_and_b64 s[6:7], s[2:3], s[4:5]
	v_cndmask_b32_e64 v0, 0, 1, s[6:7]
	v_cmp_ne_u32_e64 s[4:5], 1, v0
	s_andn2_b64 vcc, exec, s[6:7]
	v_lshrrev_b32_e32 v254, 6, v251
	s_cbranch_vccnz .LBB0_102
	s_waitcnt vmcnt(0) lgkmcnt(0)
	v_readfirstlane_b32 s88, v254
	v_readlane_b32 s89, v255, 1
	v_and_b32_e32 v0, 63, v251
	v_lshrrev_b32_e32 v1, 3, v0
	v_and_b32_e32 v2, 7, v0
	v_lshlrev_b32_e32 v7, 5, v2
	v_lshlrev_b32_e32 v2, 4, v2
	s_lshl_b32 s96, s97, 3
	s_movk_i32 s31, 0x84
	s_movk_i32 s32, 0x42
	s_add_i32 s88, s88, s96
	s_lshl_b32 s89, s89, 3
	v_lshlrev_b32_e32 v8, 14, v254
	v_mad_u32_u24 v3, v1, s31, v8
	v_add_u32_e32 v3, v3, v2
	v_mad_u32_u24 v4, v2, s32, v8
	v_lshl_add_u32 v4, v1, 2, v4
.Lcv_P0_loop:
	s_cmp_ge_u32 s88, 2816
	s_cbranch_scc1 .Lcv_P0_done
	s_mov_b32 s96, s88
	s_mul_hi_u32 s12, s96, 0x1745d18
	s_mul_i32 s31, s12, 176
	s_sub_u32 s14, s96, s31
	s_mul_i32 s31, s12, 0x160000
	s_lshl_b32 s32, s14, 7
	s_add_u32 s31, s31, s32
	s_add_u32 s90, s58, s31
	s_addc_u32 s91, s59, 0
	s_mul_i32 s31, s14, 0x10000
	s_lshl_b32 s32, s12, 7
	s_add_u32 s31, s31, s32
	s_add_u32 s31, s31, 0x200000
	s_add_u32 s92, s84, s31
	s_addc_u32 s93, s85, 0
	s_lshl_b32 s31, s12, 8
	s_add_u32 s94, s56, s31
	s_addc_u32 s95, s57, 0
	s_mov_b32 s33, 1
	s_movk_i32 s16, 0x5800
	s_movk_i32 s17, 0x800
	s_mov_b32 s29, 0x2c000
	s_mov_b32 s30, 0x4000
.Lcv_P0_body:
	v_mad_u32_u24 v5, v1, s16, v2
	v_mad_u32_u24 v6, v1, s17, v2
	s_cmp_eq_u32 s33, 0
	s_cbranch_scc1 .Lcv_P0_ng1
	global_load_dwordx4 v[72:75], v7, s[94:95]
	global_load_dwordx4 v[76:79], v7, s[94:95] offset:16
.Lcv_P0_ng1:
	global_load_dwordx4 v[8:11], v5, s[90:91] nt
	s_add_u32 s90, s90, s29
	s_addc_u32 s91, s91, 0
	global_load_dwordx4 v[12:15], v5, s[90:91] nt
	s_add_u32 s90, s90, s29
	s_addc_u32 s91, s91, 0
	global_load_dwordx4 v[16:19], v5, s[90:91] nt
	s_add_u32 s90, s90, s29
	s_addc_u32 s91, s91, 0
	global_load_dwordx4 v[20:23], v5, s[90:91] nt
	s_add_u32 s90, s90, s29
	s_addc_u32 s91, s91, 0
	global_load_dwordx4 v[24:27], v5, s[90:91] nt
	s_add_u32 s90, s90, s29
	s_addc_u32 s91, s91, 0
	global_load_dwordx4 v[28:31], v5, s[90:91] nt
	s_add_u32 s90, s90, s29
	s_addc_u32 s91, s91, 0
	global_load_dwordx4 v[32:35], v5, s[90:91] nt
	s_add_u32 s90, s90, s29
	s_addc_u32 s91, s91, 0
	global_load_dwordx4 v[36:39], v5, s[90:91] nt
	s_waitcnt vmcnt(7)
	ds_write_b32 v3, v8 offset:0
	ds_write_b32 v3, v9 offset:4
	ds_write_b32 v3, v10 offset:8
	ds_write_b32 v3, v11 offset:12
	s_waitcnt vmcnt(6)
	ds_write_b32 v3, v12 offset:1056
	ds_write_b32 v3, v13 offset:1060
	ds_write_b32 v3, v14 offset:1064
	ds_write_b32 v3, v15 offset:1068
	s_waitcnt vmcnt(5)
	ds_write_b32 v3, v16 offset:2112
	ds_write_b32 v3, v17 offset:2116
	ds_write_b32 v3, v18 offset:2120
	ds_write_b32 v3, v19 offset:2124
	s_waitcnt vmcnt(4)
	ds_write_b32 v3, v20 offset:3168
	ds_write_b32 v3, v21 offset:3172
	ds_write_b32 v3, v22 offset:3176
	ds_write_b32 v3, v23 offset:3180
	s_waitcnt vmcnt(3)
	ds_write_b32 v3, v24 offset:4224
	ds_write_b32 v3, v25 offset:4228
	ds_write_b32 v3, v26 offset:4232
	ds_write_b32 v3, v27 offset:4236
	s_waitcnt vmcnt(2)
	ds_write_b32 v3, v28 offset:5280
	ds_write_b32 v3, v29 offset:5284
	ds_write_b32 v3, v30 offset:5288
	ds_write_b32 v3, v31 offset:5292
	s_waitcnt vmcnt(1)
	ds_write_b32 v3, v32 offset:6336
	ds_write_b32 v3, v33 offset:6340
	ds_write_b32 v3, v34 offset:6344
	ds_write_b32 v3, v35 offset:6348
	s_waitcnt vmcnt(0)
	ds_write_b32 v3, v36 offset:7392
	ds_write_b32 v3, v37 offset:7396
	ds_write_b32 v3, v38 offset:7400
	ds_write_b32 v3, v39 offset:7404
	s_waitcnt lgkmcnt(0)
	ds_read2_b32 v[40:41], v4 offset0:0 offset1:33
	ds_read2_b32 v[42:43], v4 offset0:66 offset1:99
	ds_read2_b32 v[44:45], v4 offset0:132 offset1:165
	ds_read2_b32 v[46:47], v4 offset0:198 offset1:231
	ds_read2_b32 v[48:49], v4 offset0:8 offset1:41
	ds_read2_b32 v[50:51], v4 offset0:74 offset1:107
	ds_read2_b32 v[52:53], v4 offset0:140 offset1:173
	ds_read2_b32 v[54:55], v4 offset0:206 offset1:239
	ds_read2_b32 v[56:57], v4 offset0:16 offset1:49
	ds_read2_b32 v[58:59], v4 offset0:82 offset1:115
	ds_read2_b32 v[60:61], v4 offset0:148 offset1:181
	ds_read2_b32 v[62:63], v4 offset0:214 offset1:247
	ds_read2_b32 v[64:65], v4 offset0:24 offset1:57
	ds_read2_b32 v[66:67], v4 offset0:90 offset1:123
	ds_read2_b32 v[68:69], v4 offset0:156 offset1:189
	ds_read2_b32 v[70:71], v4 offset0:222 offset1:255
	s_waitcnt lgkmcnt(0)
	s_cmp_eq_u32 s33, 0
	s_cbranch_scc1 .Lcv_P0_ng2
	v_pk_mul_f32 v[40:41], v[40:41], v[72:73]
	v_pk_mul_f32 v[42:43], v[42:43], v[74:75]
	v_pk_mul_f32 v[44:45], v[44:45], v[76:77]
	v_pk_mul_f32 v[46:47], v[46:47], v[78:79]
	v_pk_mul_f32 v[48:49], v[48:49], v[72:73]
	v_pk_mul_f32 v[50:51], v[50:51], v[74:75]
	v_pk_mul_f32 v[52:53], v[52:53], v[76:77]
	v_pk_mul_f32 v[54:55], v[54:55], v[78:79]
	v_pk_mul_f32 v[56:57], v[56:57], v[72:73]
	v_pk_mul_f32 v[58:59], v[58:59], v[74:75]
	v_pk_mul_f32 v[60:61], v[60:61], v[76:77]
	v_pk_mul_f32 v[62:63], v[62:63], v[78:79]
	v_pk_mul_f32 v[64:65], v[64:65], v[72:73]
	v_pk_mul_f32 v[66:67], v[66:67], v[74:75]
	v_pk_mul_f32 v[68:69], v[68:69], v[76:77]
	v_pk_mul_f32 v[70:71], v[70:71], v[78:79]
.Lcv_P0_ng2:
	v_cvt_pk_bf16_f32 v80, v40, v41
	v_cvt_pk_bf16_f32 v81, v42, v43
	v_cvt_pk_bf16_f32 v82, v44, v45
	v_cvt_pk_bf16_f32 v83, v46, v47
	v_cvt_pk_bf16_f32 v84, v48, v49
	v_cvt_pk_bf16_f32 v85, v50, v51
	v_cvt_pk_bf16_f32 v86, v52, v53
	v_cvt_pk_bf16_f32 v87, v54, v55
	v_cvt_pk_bf16_f32 v88, v56, v57
	v_cvt_pk_bf16_f32 v89, v58, v59
	v_cvt_pk_bf16_f32 v90, v60, v61
	v_cvt_pk_bf16_f32 v91, v62, v63
	v_cvt_pk_bf16_f32 v92, v64, v65
	v_cvt_pk_bf16_f32 v93, v66, v67
	v_cvt_pk_bf16_f32 v94, v68, v69
	v_cvt_pk_bf16_f32 v95, v70, v71
	global_store_dwordx4 v6, v[80:83], s[92:93]
	s_add_u32 s92, s92, s30
	s_addc_u32 s93, s93, 0
	global_store_dwordx4 v6, v[84:87], s[92:93]
	s_add_u32 s92, s92, s30
	s_addc_u32 s93, s93, 0
	global_store_dwordx4 v6, v[88:91], s[92:93]
	s_add_u32 s92, s92, s30
	s_addc_u32 s93, s93, 0
	global_store_dwordx4 v6, v[92:95], s[92:93]
	s_add_u32 s88, s88, s89
	s_branch .Lcv_P0_loop
.Lcv_P0_done:
	v_and_b32_e32 v12, 63, v251
	s_branch .Lcv_P0_padend
	s_nop 0
	s_nop 0
	s_nop 0
	s_nop 0
	s_nop 0
	s_nop 0
	s_nop 0
	s_nop 0
	s_nop 0
.Lcv_P0_padend:
	v_lshrrev_b32_e32 v0, 4, v251
	v_and_b32_e32 v0, 60, v0
	v_lshl_add_u32 v64, s97, 5, v0
	s_mov_b32 s2, 0x8000
	v_cmp_gt_i32_e32 vcc, s2, v64
	s_and_saveexec_b64 s[8:9], vcc
	s_cbranch_execz .LBB0_101
	v_mbcnt_lo_u32_b32 v0, -1, 0
	v_mbcnt_hi_u32_b32 v0, -1, v0
	v_and_b32_e32 v1, 64, v0
	v_add_u32_e32 v1, 64, v1
	v_xor_b32_e32 v2, 1, v0
	v_cmp_lt_i32_e32 vcc, v2, v1
	s_load_dwordx2 s[10:11], s[0:1], 0xd0
	v_ashrrev_i32_e32 v65, 31, v64
	v_cndmask_b32_e32 v2, v0, v2, vcc
	v_lshlrev_b32_e32 v76, 2, v2
	v_xor_b32_e32 v2, 2, v0
	v_cmp_lt_i32_e32 vcc, v2, v1
	s_waitcnt lgkmcnt(0)
	s_lshl_b32 s10, s10, 5
	v_lshlrev_b64 v[66:67], 11, v[64:65]
	v_cndmask_b32_e32 v2, v0, v2, vcc
	v_lshlrev_b32_e32 v77, 2, v2
	v_xor_b32_e32 v2, 4, v0
	v_cmp_lt_i32_e32 vcc, v2, v1
	s_ashr_i32 s11, s10, 31
	s_mov_b64 s[14:15], 0x3c00
	v_cndmask_b32_e32 v2, v0, v2, vcc
	v_lshlrev_b32_e32 v78, 2, v2
	v_xor_b32_e32 v2, 8, v0
	v_cmp_lt_i32_e32 vcc, v2, v1
	v_cmp_eq_u32_e64 s[2:3], 0, v12
	v_lshl_or_b32 v66, v12, 3, v66
	v_cndmask_b32_e32 v2, v0, v2, vcc
	v_lshlrev_b32_e32 v79, 2, v2
	v_xor_b32_e32 v2, 16, v0
	v_cmp_lt_i32_e32 vcc, v2, v1
	s_lshl_b64 s[12:13], s[10:11], 11
	v_lshlrev_b64 v[70:71], 2, v[64:65]
	v_cndmask_b32_e32 v2, v0, v2, vcc
	v_lshlrev_b32_e32 v80, 2, v2
	v_xor_b32_e32 v2, 32, v0
	v_cmp_lt_i32_e32 vcc, v2, v1
	s_lshl_b64 s[16:17], s[10:11], 2
	s_mov_b64 s[18:19], 0
	v_cndmask_b32_e32 v0, v0, v2, vcc
	v_lshlrev_b32_e32 v81, 2, v0
	v_lshlrev_b64 v[0:1], 12, v[64:65]
	v_lshl_or_b32 v0, v12, 4, v0
	v_lshl_add_u64 v[0:1], s[52:53], 0, v[0:1]
	v_lshl_add_u64 v[68:69], v[0:1], 0, s[14:15]
	s_lshl_b64 s[14:15], s[10:11], 12
	s_movk_i32 s11, 0x7fff
	s_branch .LBB0_93

.LBB0_126:
	v_writelane_b32 v255, s68, 5
	s_load_dwordx16 s[68:83], s[0:1], 0x40
	s_load_dwordx16 s[36:51], s[0:1], 0x80
	s_and_b64 vcc, exec, s[4:5]
	s_cbranch_vccnz .LBB0_236
	s_waitcnt vmcnt(0) lgkmcnt(0)
	v_readfirstlane_b32 s88, v254
	v_readlane_b32 s89, v255, 1
	v_and_b32_e32 v0, 63, v251
	v_lshrrev_b32_e32 v1, 3, v0
	v_and_b32_e32 v2, 7, v0
	v_lshlrev_b32_e32 v7, 5, v2
	v_lshlrev_b32_e32 v2, 4, v2
	s_lshl_b32 s96, s97, 3
	s_movk_i32 s31, 0x84
	s_movk_i32 s32, 0x42
	s_add_i32 s88, s88, s96
	s_lshl_b32 s89, s89, 3
	v_lshlrev_b32_e32 v8, 14, v254
	v_mad_u32_u24 v3, v1, s31, v8
	v_add_u32_e32 v3, v3, v2
	v_mad_u32_u24 v4, v2, s32, v8
	v_lshl_add_u32 v4, v1, 2, v4
.Lcv_seam0_loop:
	s_cmp_ge_u32 s88, 1728
	s_cbranch_scc1 .Lcv_seam0_done
	s_cmp_lt_u32 s88, 512
	s_cbranch_scc1 .Lcv_seam0_job0
	s_cmp_lt_u32 s88, 1024
	s_cbranch_scc1 .Lcv_seam0_job1
	s_cmp_lt_u32 s88, 1536
	s_cbranch_scc1 .Lcv_seam0_job2
	s_cmp_lt_u32 s88, 1664
	s_cbranch_scc1 .Lcv_seam0_job3
	s_cmp_lt_u32 s88, 1696
	s_cbranch_scc1 .Lcv_seam0_job4
	s_branch .Lcv_seam0_job5
.Lcv_seam0_job0:
	s_mov_b32 s96, s88
	s_lshr_b32 s12, s96, 5
	s_and_b32 s14, s96, 31
	s_mul_i32 s31, s12, 0x40000
	s_lshl_b32 s32, s14, 7
	s_add_u32 s31, s31, s32
	s_add_u32 s90, s74, s31
	s_addc_u32 s91, s75, 0
	s_mul_i32 s31, s14, 0x10000
	s_lshl_b32 s32, s12, 7
	s_add_u32 s31, s31, s32
	s_add_u32 s31, s31, 0xd00000
	s_add_u32 s92, s84, s31
	s_addc_u32 s93, s85, 0
	s_mov_b32 s33, 0
	s_movk_i32 s16, 0x1000
	s_movk_i32 s17, 0x800
	s_mov_b32 s29, 0x8000
	s_mov_b32 s30, 0x4000
	s_branch .Lcv_seam0_body
.Lcv_seam0_job1:
	s_sub_u32 s96, s88, 512
	s_lshr_b32 s12, s96, 5
	s_and_b32 s14, s96, 31
	s_mul_i32 s31, s12, 0x40000
	s_lshl_b32 s32, s14, 7
	s_add_u32 s31, s31, s32
	s_add_u32 s90, s82, s31
	s_addc_u32 s91, s83, 0
	s_mul_i32 s31, s14, 0x10000
	s_lshl_b32 s32, s12, 7
	s_add_u32 s31, s31, s32
	s_add_u32 s31, s31, 0xf00000
	s_add_u32 s92, s84, s31
	s_addc_u32 s93, s85, 0
	s_mov_b32 s33, 0
	s_movk_i32 s16, 0x1000
	s_movk_i32 s17, 0x800
	s_mov_b32 s29, 0x8000
	s_mov_b32 s30, 0x4000
	s_branch .Lcv_seam0_body
.Lcv_seam0_job2:
	s_sub_u32 s96, s88, 1024
	s_lshr_b32 s12, s96, 5
	s_and_b32 s14, s96, 31
	s_mul_i32 s31, s12, 0x40000
	s_lshl_b32 s32, s14, 7
	s_add_u32 s31, s31, s32
	s_add_u32 s90, s36, s31
	s_addc_u32 s91, s37, 0
	s_mul_i32 s31, s14, 0x10000
	s_lshl_b32 s32, s12, 7
	s_add_u32 s31, s31, s32
	s_add_u32 s31, s31, 0x1100000
	s_add_u32 s92, s84, s31
	s_addc_u32 s93, s85, 0
	s_mov_b32 s33, 0
	s_movk_i32 s16, 0x1000
	s_movk_i32 s17, 0x800
	s_mov_b32 s29, 0x8000
	s_mov_b32 s30, 0x4000
	s_branch .Lcv_seam0_body
.Lcv_seam0_job3:
	s_sub_u32 s96, s88, 1536
	s_lshr_b32 s12, s96, 5
	s_and_b32 s14, s96, 31
	s_mul_i32 s31, s12, 0x40000
	s_lshl_b32 s32, s14, 7
	s_add_u32 s31, s31, s32
	s_add_u32 s90, s48, s31
	s_addc_u32 s91, s49, 0
	s_mul_i32 s31, s14, 0x4000
	s_lshl_b32 s32, s12, 7
	s_add_u32 s31, s31, s32
	s_add_u32 s31, s31, 0x2500000
	s_add_u32 s92, s84, s31
	s_addc_u32 s93, s85, 0
	s_mov_b32 s33, 0
	s_movk_i32 s16, 0x1000
	s_movk_i32 s17, 0x200
	s_mov_b32 s29, 0x8000
	s_mov_b32 s30, 0x1000
	s_branch .Lcv_seam0_body
.Lcv_seam0_job4:
	s_sub_u32 s96, s88, 1664
	s_lshr_b32 s12, s96, 1
	s_and_b32 s14, s96, 1
	s_mul_i32 s31, s12, 0x4000
	s_lshl_b32 s32, s14, 7
	s_add_u32 s31, s31, s32
	s_add_u32 s90, s64, s31
	s_addc_u32 s91, s65, 0
	s_lshl_b32 s31, s12, 13
	s_lshl_b32 s32, s14, 12
	s_add_u32 s31, s31, s32
	s_add_u32 s31, s31, 0x100000
	s_add_u32 s92, s84, s31
	s_addc_u32 s93, s85, 0
	s_mov_b32 s33, 0
	s_movk_i32 s16, 0x100
	s_movk_i32 s17, 0x80
	s_mov_b32 s29, 0x800
	s_mov_b32 s30, 0x400
	s_branch .Lcv_seam0_body
.Lcv_seam0_job5:
	s_sub_u32 s96, s88, 1696
	s_lshr_b32 s12, s96, 1
	s_and_b32 s14, s96, 1
	s_mul_i32 s31, s12, 0x4000
	s_lshl_b32 s32, s14, 7
	s_add_u32 s31, s31, s32
	s_add_u32 s90, s68, s31
	s_addc_u32 s91, s69, 0
	s_lshl_b32 s31, s12, 13
	s_lshl_b32 s32, s14, 12
	s_add_u32 s31, s31, s32
	s_add_u32 s31, s31, 0x120000
	s_add_u32 s92, s84, s31
	s_addc_u32 s93, s85, 0
	s_mov_b32 s33, 0
	s_movk_i32 s16, 0x100
	s_movk_i32 s17, 0x80
	s_mov_b32 s29, 0x800
	s_mov_b32 s30, 0x400

.Lcv_seam0_done:
	s_branch .Lcv_seam0_padend
	s_nop 0
	s_nop 0
	s_nop 0
	s_nop 0
	s_nop 0
	s_nop 0
	s_nop 0
	s_nop 0
	s_nop 0
	s_nop 0
	s_nop 0
	s_nop 0
	s_nop 0
	s_nop 0
	s_nop 0
	s_nop 0
	s_nop 0
	s_nop 0
	s_nop 0
	s_nop 0
	s_nop 0
	s_nop 0
.Lcv_seam0_padend:
	v_readlane_b32 s0, v255, 1
	s_waitcnt lgkmcnt(0)
	v_lshl_add_u32 v0, s97, 9, v251
	s_lshl_b32 s12, s0, 9
	s_mov_b32 s0, 0x8000
	v_readlane_b32 s1, v255, 2
	v_cmp_gt_i32_e32 vcc, s0, v0
	v_ashrrev_i32_e32 v1, 31, v0
	s_and_saveexec_b64 s[0:1], vcc
	s_cbranch_execz .LBB0_224
	v_lshl_add_u64 v[2:3], v[0:1], 2, s[84:85]
	s_mov_b64 s[4:5], 0x20000
	s_ashr_i32 s13, s12, 31
	v_lshl_add_u64 v[2:3], v[2:3], 0, s[4:5]
	s_lshl_b64 s[4:5], s[12:13], 2
	s_mov_b64 s[6:7], 0
	v_mov_b32_e32 v4, 0
	s_movk_i32 s8, 0x7fff
	v_mov_b32_e32 v5, v0

.LBB0_423:
	s_waitcnt vmcnt(0) lgkmcnt(0)
	v_readfirstlane_b32 s88, v254
	v_readlane_b32 s89, v255, 1
	v_and_b32_e32 v0, 63, v251
	v_lshrrev_b32_e32 v1, 3, v0
	v_and_b32_e32 v2, 7, v0
	v_lshlrev_b32_e32 v7, 5, v2
	v_lshlrev_b32_e32 v2, 4, v2
	s_lshl_b32 s96, s97, 3
	s_movk_i32 s31, 0x84
	s_movk_i32 s32, 0x42
	s_add_i32 s88, s88, s96
	s_lshl_b32 s89, s89, 3
	v_lshlrev_b32_e32 v8, 14, v254
	v_mad_u32_u24 v3, v1, s31, v8
	v_add_u32_e32 v3, v3, v2
	v_mad_u32_u24 v4, v2, s32, v8
	v_lshl_add_u32 v4, v1, 2, v4
.Lcv_seam2_loop:
	s_cmp_ge_u32 s88, 2048
	s_cbranch_scc1 .Lcv_seam2_done
	s_mov_b32 s96, s88
	s_lshr_b32 s12, s96, 7
	s_and_b32 s14, s96, 127
	s_mul_i32 s31, s12, 0x100000
	s_lshl_b32 s32, s14, 7
	s_add_u32 s31, s31, s32
	s_add_u32 s90, s40, s31
	s_addc_u32 s91, s41, 0
	s_mul_i32 s31, s14, 0x10000
	s_lshl_b32 s32, s12, 7
	s_add_u32 s31, s31, s32
	s_add_u32 s31, s31, 0x1300000
	s_add_u32 s92, s84, s31
	s_addc_u32 s93, s85, 0
	s_lshl_b32 s31, s12, 8
	s_add_u32 s94, s38, s31
	s_addc_u32 s95, s39, 0
	s_mov_b32 s33, 1
	s_movk_i32 s16, 0x4000
	s_movk_i32 s17, 0x800
	s_mov_b32 s29, 0x20000
	s_mov_b32 s30, 0x4000

.Lcv_seam2_done:
	s_branch .Lcv_seam2_padend
	s_nop 0
	s_nop 0
	s_nop 0
	s_nop 0
	s_nop 0
	s_nop 0
	s_nop 0
	s_nop 0
	s_nop 0
	s_nop 0
	s_nop 0
	s_nop 0
	s_nop 0
	s_nop 0
	s_nop 0
	s_nop 0
	s_nop 0
	s_nop 0
	s_nop 0
	s_nop 0
	s_nop 0
	s_nop 0
	s_nop 0
	s_nop 0
	s_nop 0
	s_nop 0
.Lcv_seam2_padend:
	s_and_b64 vcc, exec, s[2:3]
	s_cbranch_vccnz .LBB0_594
	s_branch .LBB0_578

.Lcv_seam3_loop:
	s_cmp_ge_u32 s88, 2048
	s_cbranch_scc1 .Lcv_seam3_done
	s_mov_b32 s96, s88
	s_lshr_b32 s12, s96, 5
	s_and_b32 s14, s96, 31
	s_mul_i32 s31, s12, 0x40000
	s_lshl_b32 s32, s14, 7
	s_add_u32 s31, s31, s32
	s_add_u32 s90, s42, s31
	s_addc_u32 s91, s43, 0
	s_mul_i32 s31, s14, 0x40000
	s_lshl_b32 s32, s12, 7
	s_add_u32 s31, s31, s32
	s_add_u32 s31, s31, 0x1b00000
	s_add_u32 s92, s84, s31
	s_addc_u32 s93, s85, 0
	s_mov_b32 s33, 0
	s_movk_i32 s16, 0x1000
	s_movk_i32 s17, 0x2000
	s_mov_b32 s29, 0x8000
	s_mov_b32 s30, 0x10000

.Lcv_seam3_done:
	s_branch .Lcv_seam3_padend
	s_nop 0
	s_nop 0
	s_nop 0
	s_nop 0
	s_nop 0
	s_nop 0
	s_nop 0
	s_nop 0
	s_nop 0
	s_nop 0
	s_nop 0
	s_nop 0
	s_nop 0
	s_nop 0
	s_nop 0
	s_nop 0
	s_nop 0
	s_nop 0
	s_nop 0
	s_nop 0
	s_nop 0
	s_nop 0
	s_nop 0
	s_nop 0

.Lcv_seam5_loop:
	s_cmp_ge_u32 s88, 512
	s_cbranch_scc1 .Lcv_seam5_done
	s_mov_b32 s96, s88
	s_lshr_b32 s12, s96, 5
	s_and_b32 s14, s96, 31
	s_mul_i32 s31, s12, 0x40000
	s_lshl_b32 s32, s14, 7
	s_add_u32 s31, s31, s32
	s_add_u32 s90, s46, s31
	s_addc_u32 s91, s47, 0
	s_mul_i32 s31, s14, 0x10000
	s_lshl_b32 s32, s12, 7
	s_add_u32 s31, s31, s32
	s_add_u32 s31, s31, 0x2300000
	s_add_u32 s92, s84, s31
	s_addc_u32 s93, s85, 0
	s_lshl_b32 s31, s12, 8
	s_add_u32 s94, s44, s31
	s_addc_u32 s95, s45, 0
	s_mov_b32 s33, 1
	s_movk_i32 s16, 0x1000
	s_movk_i32 s17, 0x800
	s_mov_b32 s29, 0x8000
	s_mov_b32 s30, 0x4000

.Lcv_seam5_done:
	s_branch .Lcv_seam5_padend
	s_nop 0
	s_nop 0
	s_nop 0
	s_nop 0
	s_nop 0
	s_nop 0
	s_nop 0
	s_nop 0
	s_nop 0
	s_nop 0
	s_nop 0
	s_nop 0
	s_nop 0
	s_nop 0
	s_nop 0
	s_nop 0
	s_nop 0
	s_nop 0
	s_nop 0
	s_nop 0
	s_nop 0
	s_nop 0
	s_nop 0
	s_nop 0
	s_nop 0
	s_nop 0
	s_nop 0
	s_nop 0
	s_nop 0
	s_nop 0
	s_nop 0

.LBB0_1169:
	v_lshl_add_u32 v192, s28, 8, v202
	v_ashrrev_i32_e32 v193, 31, v192
	v_lshl_add_u64 v[102:103], v[192:193], 2, s[6:7]
	v_lshl_or_b32 v188, s55, 8, v204
	global_load_dword v234, v[102:103], off
	v_ashrrev_i32_e32 v189, 31, v188
	v_lshlrev_b64 v[104:105], 10, v[192:193]
	v_lshl_add_u64 v[194:195], v[104:105], 0, v[188:189]
	v_lshlrev_b64 v[104:105], 1, v[194:195]
	v_lshl_add_u64 v[110:111], s[48:49], 0, v[104:105]
	global_load_dwordx4 v[212:215], v[110:111], off
	v_lshl_add_u64 v[110:111], s[4:5], 0, v[104:105]
	global_load_dwordx4 v[216:219], v[110:111], off
	v_or_b32_e32 v110, 16, v192
	v_ashrrev_i32_e32 v111, 31, v110
	v_or_b32_e32 v112, 32, v192
	v_or_b32_e32 v118, 48, v192
	v_lshl_add_u64 v[120:121], v[110:111], 2, s[6:7]
	v_lshlrev_b64 v[110:111], 10, v[110:111]
	v_or_b32_e32 v104, 0x100, v104
	v_ashrrev_i32_e32 v113, 31, v112
	v_ashrrev_i32_e32 v119, 31, v118
	v_lshl_add_u64 v[200:201], v[110:111], 0, v[188:189]
	v_lshl_add_u64 v[110:111], s[4:5], 0, v[104:105]
	v_lshlrev_b64 v[190:191], 12, v[192:193]
	v_lshl_add_u64 v[126:127], v[112:113], 2, s[6:7]
	v_lshl_add_u64 v[128:129], v[118:119], 2, s[6:7]
	global_load_dword v210, v[102:103], off offset:512
	global_load_dword v209, v[102:103], off offset:576
	global_load_dword v193, v[102:103], off offset:640
	global_load_dword v246, v[120:121], off
	global_load_dword v247, v[126:127], off
	global_load_dword v211, v[128:129], off
	global_load_dword v1, v[102:103], off offset:704
	v_lshl_add_u64 v[104:105], s[48:49], 0, v[104:105]
	global_load_dwordx4 v[220:223], v[110:111], off
	global_load_dwordx4 v[224:227], v[104:105], off
	v_lshlrev_b64 v[112:113], 10, v[112:113]
	v_lshlrev_b64 v[102:103], 1, v[200:201]
	v_lshlrev_b64 v[118:119], 10, v[118:119]
	v_lshl_add_u64 v[198:199], v[112:113], 0, v[188:189]
	v_lshl_add_u64 v[112:113], s[4:5], 0, v[102:103]
	v_lshl_add_u64 v[196:197], v[118:119], 0, v[188:189]
	v_lshl_add_u64 v[118:119], s[48:49], 0, v[102:103]
	global_load_dwordx4 v[170:173], v[112:113], off
	global_load_dwordx4 v[228:231], v[118:119], off
	v_lshlrev_b64 v[104:105], 1, v[198:199]
	v_lshlrev_b64 v[110:111], 1, v[196:197]
	v_or_b32_e32 v102, 0x100, v102
	v_lshl_add_u64 v[120:121], s[4:5], 0, v[104:105]
	v_lshl_add_u64 v[126:127], s[48:49], 0, v[104:105]
	v_or_b32_e32 v104, 0x100, v104
	v_lshl_add_u64 v[128:129], s[4:5], 0, v[110:111]
	v_lshl_add_u64 v[134:135], s[48:49], 0, v[110:111]
	v_or_b32_e32 v110, 0x100, v110
	v_lshl_add_u64 v[112:113], s[4:5], 0, v[102:103]
	v_lshl_add_u64 v[102:103], s[48:49], 0, v[102:103]
	v_lshl_add_u64 v[136:137], s[4:5], 0, v[104:105]
	v_lshl_add_u64 v[104:105], s[48:49], 0, v[104:105]
	v_lshl_add_u64 v[232:233], s[4:5], 0, v[110:111]
	v_lshl_add_u64 v[110:111], s[48:49], 0, v[110:111]
	global_load_dwordx4 v[150:153], v[120:121], off
	global_load_dwordx4 v[158:161], v[126:127], off
	s_nop 0
	global_load_dwordx4 v[118:121], v[128:129], off
	s_nop 0
	global_load_dwordx4 v[126:129], v[134:135], off
	global_load_dwordx4 v[162:165], v[112:113], off
	global_load_dwordx4 v[166:169], v[102:103], off
	s_nop 0
	global_load_dwordx4 v[134:137], v[136:137], off
	s_nop 0
	global_load_dwordx4 v[142:145], v[104:105], off
	s_nop 0
	global_load_dwordx4 v[102:105], v[232:233], off
	s_nop 0
	global_load_dwordx4 v[110:113], v[110:111], off
	s_waitcnt vmcnt(0)
	v_fmamk_f32 v232, v234, 0x3a800000, v208
	v_rsq_f32_e32 v240, v232
	v_lshlrev_b32_e32 v232, 16, v212
	v_and_b32_e32 v233, 0xffff0000, v212
	v_lshlrev_b32_e32 v238, 16, v218
	v_and_b32_e32 v239, 0xffff0000, v218
	v_mul_f32_e32 v218, 0xbfb8aa3b, v240
	v_pk_mul_f32 v[156:157], v[156:157], v[218:219] op_sel_hi:[1,0]
	v_pk_mul_f32 v[154:155], v[154:155], v[218:219] op_sel_hi:[1,0]
	v_exp_f32_e32 v156, v156
	v_exp_f32_e32 v154, v154
	v_exp_f32_e32 v157, v157
	v_exp_f32_e32 v155, v155
	v_pk_mul_f32 v[148:149], v[148:149], v[218:219] op_sel_hi:[1,0]
	v_pk_mul_f32 v[146:147], v[146:147], v[218:219] op_sel_hi:[1,0]
	v_exp_f32_e32 v148, v148
	v_exp_f32_e32 v146, v146
	v_exp_f32_e32 v149, v149
	v_exp_f32_e32 v147, v147
	v_pk_mul_f32 v[138:139], v[138:139], v[218:219] op_sel_hi:[1,0]
	v_pk_add_f32 v[156:157], v[156:157], 1.0 op_sel_hi:[1,0]
	v_exp_f32_e32 v138, v138
	v_exp_f32_e32 v139, v139
	v_pk_add_f32 v[154:155], v[154:155], 1.0 op_sel_hi:[1,0]
	v_rcp_f32_e32 v156, v156
	v_rcp_f32_e32 v154, v154
	v_rcp_f32_e32 v155, v155
	v_rcp_f32_e32 v157, v157
	v_pk_add_f32 v[148:149], v[148:149], 1.0 op_sel_hi:[1,0]
	v_pk_add_f32 v[146:147], v[146:147], 1.0 op_sel_hi:[1,0]
	v_pk_mul_f32 v[140:141], v[140:141], v[218:219] op_sel_hi:[1,0]
	v_pk_mul_f32 v[130:131], v[130:131], v[218:219] op_sel_hi:[1,0]
	v_rcp_f32_e32 v242, v146
	v_rcp_f32_e32 v244, v148
	v_rcp_f32_e32 v245, v149
	v_rcp_f32_e32 v243, v147
	v_exp_f32_e32 v140, v140
	v_exp_f32_e32 v141, v141
	v_pk_add_f32 v[138:139], v[138:139], 1.0 op_sel_hi:[1,0]
	v_pk_mul_f32 v[132:133], v[132:133], v[218:219] op_sel_hi:[1,0]
	v_exp_f32_e32 v130, v130
	v_exp_f32_e32 v131, v131
	v_rcp_f32_e32 v138, v138
	v_rcp_f32_e32 v139, v139
	v_exp_f32_e32 v132, v132
	v_exp_f32_e32 v133, v133
	v_lshlrev_b32_e32 v212, 16, v213
	v_and_b32_e32 v213, 0xffff0000, v213
	v_lshlrev_b32_e32 v236, 16, v216
	v_and_b32_e32 v237, 0xffff0000, v216
	v_lshlrev_b32_e32 v216, 16, v217
	v_and_b32_e32 v217, 0xffff0000, v217
	v_lshlrev_b32_e32 v234, 16, v214
	v_and_b32_e32 v235, 0xffff0000, v214
	v_lshlrev_b32_e32 v214, 16, v215
	v_and_b32_e32 v215, 0xffff0000, v215
	v_lshlrev_b32_e32 v240, 16, v219
	v_and_b32_e32 v241, 0xffff0000, v219
	v_pk_fma_f32 v[148:149], v[156:157], v[212:213], v[216:217]
	v_pk_fma_f32 v[146:147], v[154:155], v[232:233], v[236:237]
	v_lshl_add_u64 v[212:213], v[194:195], 2, s[50:51]
	v_pk_fma_f32 v[156:157], v[244:245], v[214:215], v[240:241]
	v_pk_fma_f32 v[154:155], v[242:243], v[234:235], v[238:239]
	global_store_dwordx4 v[212:213], v[146:149], off
	global_store_dwordx4 v[212:213], v[154:157], off offset:16
	v_lshlrev_b32_e32 v214, 16, v220
	v_lshlrev_b32_e32 v146, 16, v224
	v_and_b32_e32 v147, 0xffff0000, v224
	v_and_b32_e32 v215, 0xffff0000, v220
	v_pk_add_f32 v[140:141], v[140:141], 1.0 op_sel_hi:[1,0]
	v_pk_add_f32 v[130:131], v[130:131], 1.0 op_sel_hi:[1,0]
	v_rcp_f32_e32 v140, v140
	v_rcp_f32_e32 v141, v141
	v_pk_fma_f32 v[138:139], v[138:139], v[146:147], v[214:215]
	v_pk_add_f32 v[132:133], v[132:133], 1.0 op_sel_hi:[1,0]
	v_rcp_f32_e32 v130, v130
	v_rcp_f32_e32 v131, v131
	v_fmamk_f32 v146, v246, 0x3a800000, v208
	v_rcp_f32_e32 v132, v132
	v_rcp_f32_e32 v133, v133
	v_rsq_f32_e32 v146, v146
	v_lshlrev_b32_e32 v148, 16, v225
	v_and_b32_e32 v149, 0xffff0000, v225
	v_lshlrev_b32_e32 v154, 16, v226
	v_and_b32_e32 v155, 0xffff0000, v226
	v_lshlrev_b32_e32 v216, 16, v221
	v_and_b32_e32 v217, 0xffff0000, v221
	v_lshlrev_b32_e32 v220, 16, v222
	v_and_b32_e32 v221, 0xffff0000, v222
	v_lshlrev_b32_e32 v156, 16, v227
	v_and_b32_e32 v157, 0xffff0000, v227
	v_lshlrev_b32_e32 v222, 16, v223
	v_and_b32_e32 v223, 0xffff0000, v223
	v_pk_fma_f32 v[140:141], v[140:141], v[148:149], v[216:217]
	v_pk_fma_f32 v[130:131], v[130:131], v[154:155], v[220:221]
	v_pk_fma_f32 v[132:133], v[132:133], v[156:157], v[222:223]
	global_store_dwordx4 v[212:213], v[138:141], off offset:512
	global_store_dwordx4 v[212:213], v[130:133], off offset:528
	v_lshlrev_b32_e32 v148, 16, v170
	v_and_b32_e32 v149, 0xffff0000, v170
	v_mul_f32_e32 v130, 0xbfb8aa3b, v146
	v_pk_mul_f32 v[124:125], v[124:125], v[130:131] op_sel_hi:[1,0]
	v_pk_mul_f32 v[122:123], v[122:123], v[130:131] op_sel_hi:[1,0]
	v_exp_f32_e32 v124, v124
	v_exp_f32_e32 v125, v125
	v_exp_f32_e32 v122, v122
	v_exp_f32_e32 v123, v123
	v_pk_mul_f32 v[116:117], v[116:117], v[130:131] op_sel_hi:[1,0]
	v_pk_mul_f32 v[114:115], v[114:115], v[130:131] op_sel_hi:[1,0]
	v_exp_f32_e32 v116, v116
	v_exp_f32_e32 v114, v114
	v_exp_f32_e32 v117, v117
	v_exp_f32_e32 v115, v115
	v_pk_mul_f32 v[108:109], v[108:109], v[130:131] op_sel_hi:[1,0]
	v_pk_mul_f32 v[106:107], v[106:107], v[130:131] op_sel_hi:[1,0]
	v_exp_f32_e32 v108, v108
	v_exp_f32_e32 v106, v106
	v_exp_f32_e32 v109, v109
	v_exp_f32_e32 v107, v107
	v_pk_mul_f32 v[100:101], v[100:101], v[130:131] op_sel_hi:[1,0]
	v_pk_mul_f32 v[98:99], v[98:99], v[130:131] op_sel_hi:[1,0]
	v_pk_add_f32 v[124:125], v[124:125], 1.0 op_sel_hi:[1,0]
	v_exp_f32_e32 v98, v98
	v_exp_f32_e32 v100, v100
	v_exp_f32_e32 v101, v101
	v_exp_f32_e32 v99, v99
	v_pk_add_f32 v[122:123], v[122:123], 1.0 op_sel_hi:[1,0]
	v_rcp_f32_e32 v124, v124
	v_rcp_f32_e32 v125, v125
	v_rcp_f32_e32 v122, v122
	v_rcp_f32_e32 v123, v123
	v_pk_add_f32 v[116:117], v[116:117], 1.0 op_sel_hi:[1,0]
	v_pk_add_f32 v[114:115], v[114:115], 1.0 op_sel_hi:[1,0]
	v_lshlrev_b32_e32 v154, 16, v171
	v_and_b32_e32 v155, 0xffff0000, v171
	v_lshlrev_b32_e32 v156, 16, v172
	v_and_b32_e32 v157, 0xffff0000, v172
	v_lshlrev_b32_e32 v170, 16, v173
	v_and_b32_e32 v171, 0xffff0000, v173
	v_rcp_f32_e32 v172, v114
	v_rcp_f32_e32 v212, v116
	v_rcp_f32_e32 v213, v117
	v_rcp_f32_e32 v173, v115
	v_pk_add_f32 v[108:109], v[108:109], 1.0 op_sel_hi:[1,0]
	v_pk_add_f32 v[106:107], v[106:107], 1.0 op_sel_hi:[1,0]
	v_lshlrev_b32_e32 v138, 16, v229
	v_and_b32_e32 v139, 0xffff0000, v229
	v_rcp_f32_e32 v106, v106
	v_rcp_f32_e32 v107, v107
	v_rcp_f32_e32 v108, v108
	v_rcp_f32_e32 v109, v109
	v_pk_add_f32 v[100:101], v[100:101], 1.0 op_sel_hi:[1,0]
	v_pk_add_f32 v[98:99], v[98:99], 1.0 op_sel_hi:[1,0]
	v_lshlrev_b32_e32 v132, 16, v228
	v_and_b32_e32 v133, 0xffff0000, v228
	v_pk_fma_f32 v[116:117], v[124:125], v[138:139], v[154:155]
	v_rcp_f32_e32 v130, v98
	v_rcp_f32_e32 v154, v100
	v_rcp_f32_e32 v155, v101
	v_rcp_f32_e32 v131, v99
	v_lshlrev_b32_e32 v140, 16, v230
	v_and_b32_e32 v141, 0xffff0000, v230
	v_lshlrev_b32_e32 v146, 16, v231
	v_and_b32_e32 v147, 0xffff0000, v231
	v_pk_fma_f32 v[114:115], v[122:123], v[132:133], v[148:149]
	v_lshl_add_u64 v[132:133], v[200:201], 2, s[50:51]
	v_pk_fma_f32 v[124:125], v[212:213], v[146:147], v[170:171]
	v_pk_fma_f32 v[122:123], v[172:173], v[140:141], v[156:157]
	global_store_dwordx4 v[132:133], v[114:117], off
	global_store_dwordx4 v[132:133], v[122:125], off offset:16
	v_lshlrev_b32_e32 v138, 16, v162
	v_lshlrev_b32_e32 v114, 16, v166
	v_and_b32_e32 v115, 0xffff0000, v166
	v_lshlrev_b32_e32 v116, 16, v167
	v_and_b32_e32 v117, 0xffff0000, v167
	v_and_b32_e32 v139, 0xffff0000, v162
	v_lshlrev_b32_e32 v140, 16, v163
	v_and_b32_e32 v141, 0xffff0000, v163
	v_lshlrev_b32_e32 v122, 16, v168
	v_and_b32_e32 v123, 0xffff0000, v168
	v_lshlrev_b32_e32 v124, 16, v169
	v_and_b32_e32 v125, 0xffff0000, v169
	v_lshlrev_b32_e32 v146, 16, v164
	v_and_b32_e32 v147, 0xffff0000, v164
	v_lshlrev_b32_e32 v148, 16, v165
	v_and_b32_e32 v149, 0xffff0000, v165
	v_pk_fma_f32 v[100:101], v[108:109], v[116:117], v[140:141]
	v_pk_fma_f32 v[98:99], v[106:107], v[114:115], v[138:139]
	v_lshl_add_u64 v[164:165], v[194:195], 0, s[10:11]
	v_pk_fma_f32 v[108:109], v[154:155], v[124:125], v[148:149]
	v_pk_fma_f32 v[106:107], v[130:131], v[122:123], v[146:147]
	global_store_dwordx4 v[132:133], v[98:101], off offset:512
	global_store_dwordx4 v[132:133], v[106:109], off offset:528
	v_lshl_add_u64 v[162:163], v[194:195], 0, s[12:13]
	v_lshlrev_b64 v[98:99], 1, v[164:165]
	v_lshl_add_u64 v[100:101], s[4:5], 0, v[98:99]
	v_lshl_add_u64 v[106:107], s[48:49], 0, v[98:99]
	v_or_b32_e32 v98, 0x100, v98
	global_load_dwordx4 v[146:149], v[100:101], off
	global_load_dwordx4 v[154:157], v[106:107], off
	v_lshl_add_u64 v[100:101], s[4:5], 0, v[98:99]
	v_lshl_add_u64 v[98:99], s[48:49], 0, v[98:99]
	global_load_dwordx4 v[130:133], v[100:101], off
	global_load_dwordx4 v[138:141], v[98:99], off
	v_lshlrev_b64 v[98:99], 1, v[162:163]
	v_lshl_add_u64 v[100:101], s[4:5], 0, v[98:99]
	v_lshl_add_u64 v[106:107], s[48:49], 0, v[98:99]
	global_load_dwordx4 v[114:117], v[100:101], off
	global_load_dwordx4 v[122:125], v[106:107], off
	v_fmamk_f32 v106, v247, 0x3a800000, v208
	v_rsq_f32_e32 v166, v106
	v_or_b32_e32 v98, 0x100, v98
	v_lshlrev_b32_e32 v168, 16, v158
	v_and_b32_e32 v169, 0xffff0000, v158
	v_mul_f32_e32 v166, 0xbfb8aa3b, v166
	v_pk_mul_f32 v[96:97], v[96:97], v[166:167] op_sel_hi:[1,0]
	v_pk_mul_f32 v[94:95], v[94:95], v[166:167] op_sel_hi:[1,0]
	v_exp_f32_e32 v96, v96
	v_exp_f32_e32 v94, v94
	v_exp_f32_e32 v97, v97
	v_exp_f32_e32 v95, v95
	v_pk_mul_f32 v[92:93], v[92:93], v[166:167] op_sel_hi:[1,0]
	v_pk_mul_f32 v[90:91], v[90:91], v[166:167] op_sel_hi:[1,0]
	v_exp_f32_e32 v92, v92
	v_exp_f32_e32 v90, v90
	v_exp_f32_e32 v93, v93
	v_exp_f32_e32 v91, v91
	v_pk_mul_f32 v[86:87], v[86:87], v[166:167] op_sel_hi:[1,0]
	v_pk_add_f32 v[96:97], v[96:97], 1.0 op_sel_hi:[1,0]
	v_exp_f32_e32 v86, v86
	v_exp_f32_e32 v87, v87
	v_pk_add_f32 v[94:95], v[94:95], 1.0 op_sel_hi:[1,0]
	v_rcp_f32_e32 v96, v96
	v_rcp_f32_e32 v94, v94
	v_rcp_f32_e32 v95, v95
	v_rcp_f32_e32 v97, v97
	v_pk_add_f32 v[92:93], v[92:93], 1.0 op_sel_hi:[1,0]
	v_pk_add_f32 v[90:91], v[90:91], 1.0 op_sel_hi:[1,0]
	v_pk_mul_f32 v[88:89], v[88:89], v[166:167] op_sel_hi:[1,0]
	v_pk_mul_f32 v[82:83], v[82:83], v[166:167] op_sel_hi:[1,0]
	v_rcp_f32_e32 v212, v90
	v_rcp_f32_e32 v214, v92
	v_rcp_f32_e32 v215, v93
	v_rcp_f32_e32 v213, v91
	v_exp_f32_e32 v88, v88
	v_exp_f32_e32 v89, v89
	v_pk_add_f32 v[86:87], v[86:87], 1.0 op_sel_hi:[1,0]
	v_pk_mul_f32 v[84:85], v[84:85], v[166:167] op_sel_hi:[1,0]
	v_exp_f32_e32 v82, v82
	v_exp_f32_e32 v83, v83
	v_rcp_f32_e32 v86, v86
	v_rcp_f32_e32 v87, v87
	v_exp_f32_e32 v84, v84
	v_exp_f32_e32 v85, v85
	v_lshlrev_b32_e32 v158, 16, v159
	v_and_b32_e32 v159, 0xffff0000, v159
	v_lshlrev_b32_e32 v172, 16, v150
	v_and_b32_e32 v173, 0xffff0000, v150
	v_lshlrev_b32_e32 v150, 16, v151
	v_and_b32_e32 v151, 0xffff0000, v151
	v_lshl_add_u64 v[100:101], s[4:5], 0, v[98:99]
	v_lshl_add_u64 v[106:107], s[48:49], 0, v[98:99]
	v_lshlrev_b32_e32 v170, 16, v160
	v_and_b32_e32 v171, 0xffff0000, v160
	v_lshlrev_b32_e32 v160, 16, v161
	v_and_b32_e32 v161, 0xffff0000, v161
	v_lshlrev_b32_e32 v200, 16, v152
	v_and_b32_e32 v201, 0xffff0000, v152
	v_lshlrev_b32_e32 v152, 16, v153
	v_and_b32_e32 v153, 0xffff0000, v153
	v_pk_fma_f32 v[92:93], v[96:97], v[158:159], v[150:151]
	v_pk_fma_f32 v[90:91], v[94:95], v[168:169], v[172:173]
	v_lshl_add_u64 v[150:151], v[198:199], 2, s[50:51]
	global_load_dwordx4 v[98:101], v[100:101], off
	s_nop 0
	global_load_dwordx4 v[106:109], v[106:107], off
	v_pk_fma_f32 v[96:97], v[214:215], v[160:161], v[152:153]
	v_pk_fma_f32 v[94:95], v[212:213], v[170:171], v[200:201]
	global_store_dwordx4 v[150:151], v[90:93], off
	global_store_dwordx4 v[150:151], v[94:97], off offset:16
	v_pk_add_f32 v[88:89], v[88:89], 1.0 op_sel_hi:[1,0]
	v_lshlrev_b32_e32 v90, 16, v142
	v_and_b32_e32 v91, 0xffff0000, v142
	v_lshlrev_b32_e32 v92, 16, v143
	v_and_b32_e32 v93, 0xffff0000, v143
	v_lshlrev_b32_e32 v142, 16, v134
	v_and_b32_e32 v143, 0xffff0000, v134
	v_pk_add_f32 v[82:83], v[82:83], 1.0 op_sel_hi:[1,0]
	v_rcp_f32_e32 v88, v88
	v_rcp_f32_e32 v89, v89
	v_pk_fma_f32 v[86:87], v[86:87], v[90:91], v[142:143]
	v_pk_add_f32 v[84:85], v[84:85], 1.0 op_sel_hi:[1,0]
	v_rcp_f32_e32 v82, v82
	v_rcp_f32_e32 v83, v83
	v_fmamk_f32 v90, v211, 0x3a800000, v208
	v_rcp_f32_e32 v84, v84
	v_rcp_f32_e32 v85, v85
	v_rsq_f32_e32 v90, v90
	v_lshlrev_b32_e32 v94, 16, v144
	v_and_b32_e32 v95, 0xffff0000, v144
	v_lshlrev_b32_e32 v96, 16, v145
	v_and_b32_e32 v97, 0xffff0000, v145
	v_lshlrev_b32_e32 v134, 16, v135
	v_and_b32_e32 v135, 0xffff0000, v135
	v_lshlrev_b32_e32 v144, 16, v136
	v_and_b32_e32 v145, 0xffff0000, v136
	v_lshlrev_b32_e32 v136, 16, v137
	v_and_b32_e32 v137, 0xffff0000, v137
	v_pk_fma_f32 v[88:89], v[88:89], v[92:93], v[134:135]
	v_pk_fma_f32 v[82:83], v[82:83], v[94:95], v[144:145]
	v_pk_fma_f32 v[84:85], v[84:85], v[96:97], v[136:137]
	global_store_dwordx4 v[150:151], v[86:89], off offset:512
	global_store_dwordx4 v[150:151], v[82:85], off offset:528
	v_lshlrev_b32_e32 v92, 16, v118
	v_lshlrev_b32_e32 v86, 16, v127
	v_mul_f32_e32 v82, 0xbfb8aa3b, v90
	v_pk_mul_f32 v[80:81], v[80:81], v[82:83] op_sel_hi:[1,0]
	v_pk_mul_f32 v[78:79], v[78:79], v[82:83] op_sel_hi:[1,0]
	v_exp_f32_e32 v80, v80
	v_exp_f32_e32 v81, v81
	v_exp_f32_e32 v78, v78
	v_exp_f32_e32 v79, v79
	v_pk_mul_f32 v[76:77], v[76:77], v[82:83] op_sel_hi:[1,0]
	v_pk_mul_f32 v[74:75], v[74:75], v[82:83] op_sel_hi:[1,0]
	v_exp_f32_e32 v76, v76
	v_exp_f32_e32 v74, v74
	v_exp_f32_e32 v77, v77
	v_exp_f32_e32 v75, v75
	v_pk_mul_f32 v[72:73], v[72:73], v[82:83] op_sel_hi:[1,0]
	v_pk_mul_f32 v[70:71], v[70:71], v[82:83] op_sel_hi:[1,0]
	v_exp_f32_e32 v72, v72
	v_exp_f32_e32 v70, v70
	v_exp_f32_e32 v73, v73
	v_exp_f32_e32 v71, v71
	v_pk_mul_f32 v[68:69], v[68:69], v[82:83] op_sel_hi:[1,0]
	v_pk_mul_f32 v[66:67], v[66:67], v[82:83] op_sel_hi:[1,0]
	v_pk_add_f32 v[80:81], v[80:81], 1.0 op_sel_hi:[1,0]
	v_exp_f32_e32 v66, v66
	v_exp_f32_e32 v68, v68
	v_exp_f32_e32 v69, v69
	v_exp_f32_e32 v67, v67
	v_pk_add_f32 v[78:79], v[78:79], 1.0 op_sel_hi:[1,0]
	v_rcp_f32_e32 v80, v80
	v_rcp_f32_e32 v81, v81
	v_rcp_f32_e32 v78, v78
	v_rcp_f32_e32 v79, v79
	v_pk_add_f32 v[76:77], v[76:77], 1.0 op_sel_hi:[1,0]
	v_pk_add_f32 v[74:75], v[74:75], 1.0 op_sel_hi:[1,0]
	v_lshlrev_b32_e32 v84, 16, v126
	v_and_b32_e32 v85, 0xffff0000, v126
	v_and_b32_e32 v87, 0xffff0000, v127
	v_and_b32_e32 v93, 0xffff0000, v118
	v_lshlrev_b32_e32 v94, 16, v119
	v_and_b32_e32 v95, 0xffff0000, v119
	v_lshlrev_b32_e32 v96, 16, v120
	v_and_b32_e32 v97, 0xffff0000, v120
	v_lshlrev_b32_e32 v118, 16, v121
	v_and_b32_e32 v119, 0xffff0000, v121
	v_rcp_f32_e32 v120, v74
	v_rcp_f32_e32 v126, v76
	v_rcp_f32_e32 v127, v77
	v_rcp_f32_e32 v121, v75
	v_pk_add_f32 v[72:73], v[72:73], 1.0 op_sel_hi:[1,0]
	v_pk_add_f32 v[70:71], v[70:71], 1.0 op_sel_hi:[1,0]
	v_rcp_f32_e32 v72, v72
	v_rcp_f32_e32 v70, v70
	v_rcp_f32_e32 v71, v71
	v_rcp_f32_e32 v73, v73
	v_pk_add_f32 v[68:69], v[68:69], 1.0 op_sel_hi:[1,0]
	v_pk_add_f32 v[66:67], v[66:67], 1.0 op_sel_hi:[1,0]
	v_pk_fma_f32 v[76:77], v[80:81], v[86:87], v[94:95]
	v_rcp_f32_e32 v82, v66
	v_rcp_f32_e32 v94, v68
	v_rcp_f32_e32 v95, v69
	v_rcp_f32_e32 v83, v67
	v_lshlrev_b32_e32 v88, 16, v128
	v_and_b32_e32 v89, 0xffff0000, v128
	v_lshlrev_b32_e32 v90, 16, v129
	v_and_b32_e32 v91, 0xffff0000, v129
	v_pk_fma_f32 v[74:75], v[78:79], v[84:85], v[92:93]
	v_lshl_add_u64 v[84:85], v[196:197], 2, s[50:51]
	v_pk_fma_f32 v[80:81], v[126:127], v[90:91], v[118:119]
	v_pk_fma_f32 v[78:79], v[120:121], v[88:89], v[96:97]
	global_store_dwordx4 v[84:85], v[74:77], off
	global_store_dwordx4 v[84:85], v[78:81], off offset:16
	v_lshlrev_b32_e32 v86, 16, v102
	v_lshlrev_b32_e32 v74, 16, v110
	v_and_b32_e32 v75, 0xffff0000, v110
	v_lshlrev_b32_e32 v76, 16, v111
	v_and_b32_e32 v77, 0xffff0000, v111
	v_and_b32_e32 v87, 0xffff0000, v102
	v_lshlrev_b32_e32 v88, 16, v103
	v_and_b32_e32 v89, 0xffff0000, v103
	v_lshlrev_b32_e32 v78, 16, v112
	v_and_b32_e32 v79, 0xffff0000, v112
	v_lshlrev_b32_e32 v80, 16, v113
	v_and_b32_e32 v81, 0xffff0000, v113
	v_lshlrev_b32_e32 v90, 16, v104
	v_and_b32_e32 v91, 0xffff0000, v104
	v_lshlrev_b32_e32 v92, 16, v105
	v_and_b32_e32 v93, 0xffff0000, v105
	v_pk_fma_f32 v[68:69], v[72:73], v[76:77], v[88:89]
	v_pk_fma_f32 v[66:67], v[70:71], v[74:75], v[86:87]
	v_pk_fma_f32 v[72:73], v[94:95], v[80:81], v[92:93]
	v_pk_fma_f32 v[70:71], v[82:83], v[78:79], v[90:91]
	global_store_dwordx4 v[84:85], v[66:69], off offset:512
	global_store_dwordx4 v[84:85], v[70:73], off offset:528
	v_lshl_add_u64 v[102:103], v[194:195], 0, s[14:15]
	v_add_u32_e32 v66, 0xa0, v192
	v_ashrrev_i32_e32 v67, 31, v66
	v_lshlrev_b64 v[66:67], 10, v[66:67]
	v_lshl_add_u64 v[66:67], v[66:67], 0, v[188:189]
	v_lshlrev_b64 v[66:67], 1, v[66:67]
	v_lshl_add_u64 v[68:69], s[4:5], 0, v[66:67]
	v_lshl_add_u64 v[70:71], s[48:49], 0, v[66:67]
	global_load_dwordx4 v[90:93], v[68:69], off
	global_load_dwordx4 v[94:97], v[70:71], off
	v_or_b32_e32 v66, 0x100, v66
	v_lshl_add_u64 v[68:69], s[4:5], 0, v[66:67]
	v_lshl_add_u64 v[66:67], s[48:49], 0, v[66:67]
	global_load_dwordx4 v[82:85], v[68:69], off
	global_load_dwordx4 v[86:89], v[66:67], off
	v_lshlrev_b64 v[66:67], 1, v[102:103]
	v_lshl_add_u64 v[68:69], s[4:5], 0, v[66:67]
	v_lshl_add_u64 v[70:71], s[48:49], 0, v[66:67]
	global_load_dwordx4 v[74:77], v[68:69], off
	global_load_dwordx4 v[78:81], v[70:71], off
	v_or_b32_e32 v66, 0x100, v66
	v_fmamk_f32 v70, v210, 0x3a800000, v208
	v_lshl_add_u64 v[68:69], s[4:5], 0, v[66:67]
	v_rsq_f32_e32 v104, v70
	v_lshl_add_u64 v[70:71], s[48:49], 0, v[66:67]
	global_load_dwordx4 v[66:69], v[68:69], off
	s_nop 0
	global_load_dwordx4 v[70:73], v[70:71], off
	s_waitcnt vmcnt(22)
	v_lshlrev_b32_e32 v110, 16, v154
	v_mul_f32_e32 v104, 0xbfb8aa3b, v104
	v_pk_mul_f32 v[64:65], v[64:65], v[104:105] op_sel_hi:[1,0]
	v_pk_mul_f32 v[62:63], v[62:63], v[104:105] op_sel_hi:[1,0]
	v_exp_f32_e32 v64, v64
	v_exp_f32_e32 v62, v62
	v_exp_f32_e32 v65, v65
	v_exp_f32_e32 v63, v63
	v_pk_mul_f32 v[60:61], v[60:61], v[104:105] op_sel_hi:[1,0]
	v_pk_mul_f32 v[58:59], v[58:59], v[104:105] op_sel_hi:[1,0]
	v_exp_f32_e32 v60, v60
	v_exp_f32_e32 v58, v58
	v_exp_f32_e32 v61, v61
	v_exp_f32_e32 v59, v59
	v_pk_mul_f32 v[54:55], v[54:55], v[104:105] op_sel_hi:[1,0]
	v_pk_add_f32 v[64:65], v[64:65], 1.0 op_sel_hi:[1,0]
	v_exp_f32_e32 v54, v54
	v_exp_f32_e32 v55, v55
	v_pk_add_f32 v[62:63], v[62:63], 1.0 op_sel_hi:[1,0]
	v_rcp_f32_e32 v64, v64
	v_rcp_f32_e32 v62, v62
	v_rcp_f32_e32 v63, v63
	v_rcp_f32_e32 v65, v65
	v_pk_add_f32 v[60:61], v[60:61], 1.0 op_sel_hi:[1,0]
	v_pk_add_f32 v[58:59], v[58:59], 1.0 op_sel_hi:[1,0]
	v_pk_mul_f32 v[56:57], v[56:57], v[104:105] op_sel_hi:[1,0]
	v_pk_mul_f32 v[50:51], v[50:51], v[104:105] op_sel_hi:[1,0]
	v_rcp_f32_e32 v142, v58
	v_rcp_f32_e32 v144, v60
	v_rcp_f32_e32 v145, v61
	v_rcp_f32_e32 v143, v59
	v_exp_f32_e32 v56, v56
	v_exp_f32_e32 v57, v57
	v_pk_add_f32 v[54:55], v[54:55], 1.0 op_sel_hi:[1,0]
	v_pk_mul_f32 v[52:53], v[52:53], v[104:105] op_sel_hi:[1,0]
	v_exp_f32_e32 v50, v50
	v_exp_f32_e32 v51, v51
	v_rcp_f32_e32 v54, v54
	v_rcp_f32_e32 v55, v55
	v_exp_f32_e32 v52, v52
	v_exp_f32_e32 v53, v53
	v_and_b32_e32 v111, 0xffff0000, v154
	v_lshlrev_b32_e32 v112, 16, v155
	v_and_b32_e32 v113, 0xffff0000, v155
	v_lshlrev_b32_e32 v126, 16, v146
	v_and_b32_e32 v127, 0xffff0000, v146
	v_lshlrev_b32_e32 v128, 16, v147
	v_and_b32_e32 v129, 0xffff0000, v147
	v_lshlrev_b32_e32 v118, 16, v156
	v_and_b32_e32 v119, 0xffff0000, v156
	v_lshlrev_b32_e32 v120, 16, v157
	v_and_b32_e32 v121, 0xffff0000, v157
	v_lshlrev_b32_e32 v134, 16, v148
	v_and_b32_e32 v135, 0xffff0000, v148
	v_lshlrev_b32_e32 v136, 16, v149
	v_and_b32_e32 v137, 0xffff0000, v149
	v_pk_fma_f32 v[60:61], v[64:65], v[112:113], v[128:129]
	v_pk_fma_f32 v[58:59], v[62:63], v[110:111], v[126:127]
	v_lshl_add_u64 v[110:111], v[164:165], 2, s[50:51]
	v_pk_fma_f32 v[64:65], v[144:145], v[120:121], v[136:137]
	v_pk_fma_f32 v[62:63], v[142:143], v[118:119], v[134:135]
	global_store_dwordx4 v[110:111], v[58:61], off
	global_store_dwordx4 v[110:111], v[62:65], off offset:16
	s_waitcnt vmcnt(23)
	v_lshlrev_b32_e32 v112, 16, v130
	s_waitcnt vmcnt(22)
	v_lshlrev_b32_e32 v58, 16, v138
	v_and_b32_e32 v59, 0xffff0000, v138
	v_and_b32_e32 v113, 0xffff0000, v130
	v_pk_add_f32 v[56:57], v[56:57], 1.0 op_sel_hi:[1,0]
	v_pk_add_f32 v[50:51], v[50:51], 1.0 op_sel_hi:[1,0]
	v_rcp_f32_e32 v56, v56
	v_rcp_f32_e32 v57, v57
	v_pk_fma_f32 v[54:55], v[54:55], v[58:59], v[112:113]
	v_pk_add_f32 v[52:53], v[52:53], 1.0 op_sel_hi:[1,0]
	v_rcp_f32_e32 v50, v50
	v_rcp_f32_e32 v51, v51
	v_fmamk_f32 v58, v209, 0x3a800000, v208
	v_rcp_f32_e32 v52, v52
	v_rcp_f32_e32 v53, v53
	v_rsq_f32_e32 v58, v58
	v_lshlrev_b32_e32 v60, 16, v139
	v_and_b32_e32 v61, 0xffff0000, v139
	v_lshlrev_b32_e32 v62, 16, v140
	v_and_b32_e32 v63, 0xffff0000, v140
	v_lshlrev_b32_e32 v118, 16, v131
	v_and_b32_e32 v119, 0xffff0000, v131
	v_lshlrev_b32_e32 v120, 16, v132
	v_and_b32_e32 v121, 0xffff0000, v132
	v_lshlrev_b32_e32 v64, 16, v141
	v_and_b32_e32 v65, 0xffff0000, v141
	v_lshlrev_b32_e32 v126, 16, v133
	v_and_b32_e32 v127, 0xffff0000, v133
	v_pk_fma_f32 v[56:57], v[56:57], v[60:61], v[118:119]
	v_pk_fma_f32 v[50:51], v[50:51], v[62:63], v[120:121]
	v_pk_fma_f32 v[52:53], v[52:53], v[64:65], v[126:127]
	global_store_dwordx4 v[110:111], v[54:57], off offset:512
	global_store_dwordx4 v[110:111], v[50:53], off offset:528
	s_waitcnt vmcnt(23)
	v_lshlrev_b32_e32 v60, 16, v114
	s_waitcnt vmcnt(22)
	v_lshlrev_b32_e32 v54, 16, v123
	v_mul_f32_e32 v50, 0xbfb8aa3b, v58
	v_pk_mul_f32 v[48:49], v[48:49], v[50:51] op_sel_hi:[1,0]
	v_pk_mul_f32 v[46:47], v[46:47], v[50:51] op_sel_hi:[1,0]
	v_exp_f32_e32 v48, v48
	v_exp_f32_e32 v46, v46
	v_exp_f32_e32 v49, v49
	v_exp_f32_e32 v47, v47
	v_pk_mul_f32 v[44:45], v[44:45], v[50:51] op_sel_hi:[1,0]
	v_pk_mul_f32 v[42:43], v[42:43], v[50:51] op_sel_hi:[1,0]
	v_exp_f32_e32 v44, v44
	v_exp_f32_e32 v42, v42
	v_exp_f32_e32 v45, v45
	v_exp_f32_e32 v43, v43
	v_pk_mul_f32 v[38:39], v[38:39], v[50:51] op_sel_hi:[1,0]
	v_pk_add_f32 v[48:49], v[48:49], 1.0 op_sel_hi:[1,0]
	v_exp_f32_e32 v38, v38
	v_exp_f32_e32 v39, v39
	v_pk_add_f32 v[46:47], v[46:47], 1.0 op_sel_hi:[1,0]
	v_rcp_f32_e32 v48, v48
	v_rcp_f32_e32 v46, v46
	v_rcp_f32_e32 v47, v47
	v_rcp_f32_e32 v49, v49
	v_pk_add_f32 v[44:45], v[44:45], 1.0 op_sel_hi:[1,0]
	v_pk_add_f32 v[42:43], v[42:43], 1.0 op_sel_hi:[1,0]
	v_pk_mul_f32 v[40:41], v[40:41], v[50:51] op_sel_hi:[1,0]
	v_pk_mul_f32 v[34:35], v[34:35], v[50:51] op_sel_hi:[1,0]
	v_rcp_f32_e32 v110, v42
	v_rcp_f32_e32 v112, v44
	v_rcp_f32_e32 v113, v45
	v_rcp_f32_e32 v111, v43
	v_exp_f32_e32 v40, v40
	v_exp_f32_e32 v41, v41
	v_pk_add_f32 v[38:39], v[38:39], 1.0 op_sel_hi:[1,0]
	v_pk_mul_f32 v[36:37], v[36:37], v[50:51] op_sel_hi:[1,0]
	v_exp_f32_e32 v34, v34
	v_exp_f32_e32 v35, v35
	v_rcp_f32_e32 v38, v38
	v_rcp_f32_e32 v39, v39
	v_exp_f32_e32 v36, v36
	v_exp_f32_e32 v37, v37
	v_lshlrev_b32_e32 v52, 16, v122
	v_and_b32_e32 v53, 0xffff0000, v122
	v_and_b32_e32 v55, 0xffff0000, v123
	v_and_b32_e32 v61, 0xffff0000, v114
	v_lshlrev_b32_e32 v62, 16, v115
	v_and_b32_e32 v63, 0xffff0000, v115
	v_lshlrev_b32_e32 v56, 16, v124
	v_and_b32_e32 v57, 0xffff0000, v124
	v_lshlrev_b32_e32 v58, 16, v125
	v_and_b32_e32 v59, 0xffff0000, v125
	v_lshlrev_b32_e32 v64, 16, v116
	v_and_b32_e32 v65, 0xffff0000, v116
	v_lshlrev_b32_e32 v104, 16, v117
	v_and_b32_e32 v105, 0xffff0000, v117
	v_pk_fma_f32 v[44:45], v[48:49], v[54:55], v[62:63]
	v_pk_fma_f32 v[42:43], v[46:47], v[52:53], v[60:61]
	v_lshl_add_u64 v[52:53], v[162:163], 2, s[50:51]
	v_pk_fma_f32 v[48:49], v[112:113], v[58:59], v[104:105]
	v_pk_fma_f32 v[46:47], v[110:111], v[56:57], v[64:65]
	global_store_dwordx4 v[52:53], v[42:45], off
	global_store_dwordx4 v[52:53], v[46:49], off offset:16
	s_waitcnt vmcnt(23)
	v_lshlrev_b32_e32 v54, 16, v98
	s_waitcnt vmcnt(22)
	v_lshlrev_b32_e32 v42, 16, v106
	v_and_b32_e32 v43, 0xffff0000, v106
	v_and_b32_e32 v55, 0xffff0000, v98
	v_pk_add_f32 v[40:41], v[40:41], 1.0 op_sel_hi:[1,0]
	v_pk_add_f32 v[34:35], v[34:35], 1.0 op_sel_hi:[1,0]
	v_rcp_f32_e32 v40, v40
	v_rcp_f32_e32 v41, v41
	v_pk_fma_f32 v[38:39], v[38:39], v[42:43], v[54:55]
	v_pk_add_f32 v[36:37], v[36:37], 1.0 op_sel_hi:[1,0]
	v_rcp_f32_e32 v34, v34
	v_rcp_f32_e32 v35, v35
	v_fmamk_f32 v42, v193, 0x3a800000, v208
	v_rcp_f32_e32 v36, v36
	v_rcp_f32_e32 v37, v37
	v_rsq_f32_e32 v42, v42
	v_lshlrev_b32_e32 v44, 16, v107
	v_and_b32_e32 v45, 0xffff0000, v107
	v_lshlrev_b32_e32 v46, 16, v108
	v_and_b32_e32 v47, 0xffff0000, v108
	v_lshlrev_b32_e32 v56, 16, v99
	v_and_b32_e32 v57, 0xffff0000, v99
	v_lshlrev_b32_e32 v58, 16, v100
	v_and_b32_e32 v59, 0xffff0000, v100
	v_lshlrev_b32_e32 v48, 16, v109
	v_and_b32_e32 v49, 0xffff0000, v109
	v_lshlrev_b32_e32 v60, 16, v101
	v_and_b32_e32 v61, 0xffff0000, v101
	v_pk_fma_f32 v[40:41], v[40:41], v[44:45], v[56:57]
	v_pk_fma_f32 v[34:35], v[34:35], v[46:47], v[58:59]
	v_pk_fma_f32 v[36:37], v[36:37], v[48:49], v[60:61]
	global_store_dwordx4 v[52:53], v[38:41], off offset:512
	global_store_dwordx4 v[52:53], v[34:37], off offset:528
	s_waitcnt vmcnt(15)
	v_lshlrev_b32_e32 v44, 16, v90
	v_and_b32_e32 v45, 0xffff0000, v90
	v_mul_f32_e32 v34, 0xbfb8aa3b, v42
	v_pk_mul_f32 v[30:31], v[30:31], v[34:35] op_sel_hi:[1,0]
	v_pk_mul_f32 v[32:33], v[32:33], v[34:35] op_sel_hi:[1,0]
	v_exp_f32_e32 v30, v30
	v_exp_f32_e32 v31, v31
	v_exp_f32_e32 v32, v32
	v_exp_f32_e32 v33, v33
	v_pk_mul_f32 v[26:27], v[26:27], v[34:35] op_sel_hi:[1,0]
	v_pk_mul_f32 v[28:29], v[28:29], v[34:35] op_sel_hi:[1,0]
	v_exp_f32_e32 v26, v26
	v_exp_f32_e32 v27, v27
	v_pk_add_f32 v[30:31], v[30:31], 1.0 op_sel_hi:[1,0]
	v_exp_f32_e32 v28, v28
	v_exp_f32_e32 v29, v29
	v_pk_mul_f32 v[24:25], v[24:25], v[34:35] op_sel_hi:[1,0]
	v_pk_mul_f32 v[22:23], v[22:23], v[34:35] op_sel_hi:[1,0]
	v_pk_mul_f32 v[18:19], v[18:19], v[34:35] op_sel_hi:[1,0]
	v_rcp_f32_e32 v30, v30
	v_rcp_f32_e32 v31, v31
	v_exp_f32_e32 v22, v22
	v_exp_f32_e32 v24, v24
	v_exp_f32_e32 v25, v25
	v_exp_f32_e32 v23, v23
	v_pk_mul_f32 v[20:21], v[20:21], v[34:35] op_sel_hi:[1,0]
	v_exp_f32_e32 v18, v18
	v_exp_f32_e32 v19, v19
	v_pk_add_f32 v[32:33], v[32:33], 1.0 op_sel_hi:[1,0]
	v_exp_f32_e32 v20, v20
	v_exp_f32_e32 v21, v21
	v_rcp_f32_e32 v32, v32
	v_rcp_f32_e32 v33, v33
	v_pk_add_f32 v[26:27], v[26:27], 1.0 op_sel_hi:[1,0]
	s_waitcnt vmcnt(14)
	v_lshlrev_b32_e32 v36, 16, v94
	v_and_b32_e32 v37, 0xffff0000, v94
	v_pk_add_f32 v[28:29], v[28:29], 1.0 op_sel_hi:[1,0]
	v_rcp_f32_e32 v52, v26
	v_rcp_f32_e32 v53, v27
	v_rcp_f32_e32 v54, v28
	v_rcp_f32_e32 v55, v29
	v_pk_fma_f32 v[26:27], v[30:31], v[36:37], v[44:45]
	v_lshl_add_u64 v[36:37], s[50:51], 0, v[190:191]
	v_pk_add_f32 v[24:25], v[24:25], 1.0 op_sel_hi:[1,0]
	v_pk_add_f32 v[22:23], v[22:23], 1.0 op_sel_hi:[1,0]
	v_pk_add_f32 v[18:19], v[18:19], 1.0 op_sel_hi:[1,0]
	v_lshlrev_b32_e32 v38, 16, v95
	v_and_b32_e32 v39, 0xffff0000, v95
	v_lshlrev_b32_e32 v46, 16, v91
	v_and_b32_e32 v47, 0xffff0000, v91
	v_lshl_add_u64 v[36:37], v[188:189], 2, v[36:37]
	v_rcp_f32_e32 v22, v22
	v_rcp_f32_e32 v24, v24
	v_rcp_f32_e32 v25, v25
	v_rcp_f32_e32 v23, v23
	v_pk_add_f32 v[20:21], v[20:21], 1.0 op_sel_hi:[1,0]
	v_rcp_f32_e32 v18, v18
	v_rcp_f32_e32 v19, v19
	v_fmamk_f32 v1, v1, 0x3a800000, v208
	v_lshlrev_b32_e32 v40, 16, v96
	v_and_b32_e32 v41, 0xffff0000, v96
	v_lshlrev_b32_e32 v48, 16, v92
	v_and_b32_e32 v49, 0xffff0000, v92
	v_pk_fma_f32 v[28:29], v[32:33], v[38:39], v[46:47]
	v_lshl_add_u64 v[38:39], v[36:37], 0, s[16:17]
	v_add_co_u32_e32 v36, vcc, s54, v36
	v_rcp_f32_e32 v20, v20
	v_rcp_f32_e32 v21, v21
	v_rsq_f32_e32 v1, v1
	v_lshlrev_b32_e32 v42, 16, v97
	v_and_b32_e32 v43, 0xffff0000, v97
	v_lshlrev_b32_e32 v50, 16, v93
	v_and_b32_e32 v51, 0xffff0000, v93
	v_pk_fma_f32 v[30:31], v[52:53], v[40:41], v[48:49]
	v_addc_co_u32_e32 v37, vcc, 0, v37, vcc
	v_pk_fma_f32 v[32:33], v[54:55], v[42:43], v[50:51]
	global_store_dwordx4 v[36:37], v[26:29], off
	global_store_dwordx4 v[38:39], v[30:33], off offset:16
	s_waitcnt vmcnt(15)
	v_lshlrev_b32_e32 v36, 16, v82
	s_waitcnt vmcnt(14)
	v_lshlrev_b32_e32 v26, 16, v86
	v_and_b32_e32 v27, 0xffff0000, v86
	v_lshlrev_b32_e32 v28, 16, v87
	v_and_b32_e32 v29, 0xffff0000, v87
	v_lshlrev_b32_e32 v30, 16, v88
	v_and_b32_e32 v31, 0xffff0000, v88
	v_and_b32_e32 v37, 0xffff0000, v82
	v_lshlrev_b32_e32 v40, 16, v83
	v_and_b32_e32 v41, 0xffff0000, v83
	v_lshlrev_b32_e32 v42, 16, v84
	v_and_b32_e32 v43, 0xffff0000, v84
	v_lshlrev_b32_e32 v32, 16, v89
	v_and_b32_e32 v33, 0xffff0000, v89
	v_lshlrev_b32_e32 v44, 16, v85
	v_and_b32_e32 v45, 0xffff0000, v85
	v_pk_fma_f32 v[24:25], v[24:25], v[28:29], v[40:41]
	v_pk_fma_f32 v[22:23], v[22:23], v[26:27], v[36:37]
	v_pk_fma_f32 v[18:19], v[18:19], v[30:31], v[42:43]
	v_pk_fma_f32 v[20:21], v[20:21], v[32:33], v[44:45]
	global_store_dwordx4 v[38:39], v[22:25], off offset:512
	global_store_dwordx4 v[38:39], v[18:21], off offset:528
	s_waitcnt vmcnt(15)
	v_lshlrev_b32_e32 v30, 16, v75
	s_waitcnt vmcnt(14)
	v_lshlrev_b32_e32 v22, 16, v79
	v_mul_f32_e32 v18, 0xbfb8aa3b, v1
	v_pk_mul_f32 v[16:17], v[16:17], v[18:19] op_sel_hi:[1,0]
	v_pk_mul_f32 v[14:15], v[14:15], v[18:19] op_sel_hi:[1,0]
	v_exp_f32_e32 v16, v16
	v_exp_f32_e32 v17, v17
	v_exp_f32_e32 v14, v14
	v_exp_f32_e32 v15, v15
	v_pk_mul_f32 v[12:13], v[12:13], v[18:19] op_sel_hi:[1,0]
	v_pk_mul_f32 v[10:11], v[10:11], v[18:19] op_sel_hi:[1,0]
	v_exp_f32_e32 v12, v12
	v_exp_f32_e32 v10, v10
	v_exp_f32_e32 v13, v13
	v_exp_f32_e32 v11, v11
	v_pk_mul_f32 v[8:9], v[8:9], v[18:19] op_sel_hi:[1,0]
	v_pk_mul_f32 v[6:7], v[6:7], v[18:19] op_sel_hi:[1,0]
	v_exp_f32_e32 v8, v8
	v_exp_f32_e32 v6, v6
	v_exp_f32_e32 v9, v9
	v_exp_f32_e32 v7, v7
	v_pk_mul_f32 v[4:5], v[4:5], v[18:19] op_sel_hi:[1,0]
	v_pk_mul_f32 v[2:3], v[2:3], v[18:19] op_sel_hi:[1,0]
	v_pk_add_f32 v[16:17], v[16:17], 1.0 op_sel_hi:[1,0]
	v_exp_f32_e32 v2, v2
	v_exp_f32_e32 v4, v4
	v_exp_f32_e32 v5, v5
	v_exp_f32_e32 v3, v3
	v_pk_add_f32 v[14:15], v[14:15], 1.0 op_sel_hi:[1,0]
	v_rcp_f32_e32 v16, v16
	v_rcp_f32_e32 v17, v17
	v_rcp_f32_e32 v14, v14
	v_rcp_f32_e32 v15, v15
	v_pk_add_f32 v[12:13], v[12:13], 1.0 op_sel_hi:[1,0]
	v_pk_add_f32 v[10:11], v[10:11], 1.0 op_sel_hi:[1,0]
	v_rcp_f32_e32 v38, v12
	v_rcp_f32_e32 v36, v10
	v_rcp_f32_e32 v39, v13
	v_rcp_f32_e32 v37, v11
	v_pk_add_f32 v[8:9], v[8:9], 1.0 op_sel_hi:[1,0]
	v_pk_add_f32 v[6:7], v[6:7], 1.0 op_sel_hi:[1,0]
	v_and_b32_e32 v23, 0xffff0000, v79
	v_and_b32_e32 v31, 0xffff0000, v75
	v_rcp_f32_e32 v6, v6
	v_rcp_f32_e32 v7, v7
	v_rcp_f32_e32 v8, v8
	v_rcp_f32_e32 v9, v9
	v_pk_add_f32 v[4:5], v[4:5], 1.0 op_sel_hi:[1,0]
	v_pk_add_f32 v[2:3], v[2:3], 1.0 op_sel_hi:[1,0]
	v_lshlrev_b32_e32 v20, 16, v78
	v_and_b32_e32 v21, 0xffff0000, v78
	v_lshlrev_b32_e32 v28, 16, v74
	v_and_b32_e32 v29, 0xffff0000, v74
	v_pk_fma_f32 v[12:13], v[16:17], v[22:23], v[30:31]
	v_rcp_f32_e32 v18, v2
	v_rcp_f32_e32 v30, v4
	v_rcp_f32_e32 v31, v5
	v_rcp_f32_e32 v19, v3
	v_lshlrev_b32_e32 v24, 16, v80
	v_and_b32_e32 v25, 0xffff0000, v80
	v_lshlrev_b32_e32 v26, 16, v81
	v_and_b32_e32 v27, 0xffff0000, v81
	v_lshlrev_b32_e32 v32, 16, v76
	v_and_b32_e32 v33, 0xffff0000, v76
	v_lshlrev_b32_e32 v34, 16, v77
	v_and_b32_e32 v35, 0xffff0000, v77
	v_pk_fma_f32 v[10:11], v[14:15], v[20:21], v[28:29]
	v_lshl_add_u64 v[20:21], v[102:103], 2, s[50:51]
	v_pk_fma_f32 v[16:17], v[38:39], v[26:27], v[34:35]
	v_pk_fma_f32 v[14:15], v[36:37], v[24:25], v[32:33]
	global_store_dwordx4 v[20:21], v[10:13], off
	global_store_dwordx4 v[20:21], v[14:17], off offset:16
	s_waitcnt vmcnt(15)
	v_lshlrev_b32_e32 v22, 16, v66
	s_waitcnt vmcnt(14)
	v_lshlrev_b32_e32 v10, 16, v70
	v_and_b32_e32 v11, 0xffff0000, v70
	v_lshlrev_b32_e32 v12, 16, v71
	v_and_b32_e32 v13, 0xffff0000, v71
	v_and_b32_e32 v23, 0xffff0000, v66
	v_lshlrev_b32_e32 v24, 16, v67
	v_and_b32_e32 v25, 0xffff0000, v67
	v_lshlrev_b32_e32 v14, 16, v72
	v_and_b32_e32 v15, 0xffff0000, v72
	v_lshlrev_b32_e32 v16, 16, v73
	v_and_b32_e32 v17, 0xffff0000, v73
	v_lshlrev_b32_e32 v26, 16, v68
	v_and_b32_e32 v27, 0xffff0000, v68
	v_lshlrev_b32_e32 v28, 16, v69
	v_and_b32_e32 v29, 0xffff0000, v69
	v_pk_fma_f32 v[4:5], v[8:9], v[12:13], v[24:25]
	v_pk_fma_f32 v[2:3], v[6:7], v[10:11], v[22:23]
	s_andn2_b64 vcc, exec, s[24:25]
	s_mov_b64 s[24:25], -1
	v_pk_fma_f32 v[8:9], v[30:31], v[16:17], v[28:29]
	v_pk_fma_f32 v[6:7], v[18:19], v[14:15], v[26:27]
	global_store_dwordx4 v[20:21], v[2:5], off offset:512
	global_store_dwordx4 v[20:21], v[6:9], off offset:528
	s_cbranch_vccnz .LBB0_1157
	v_mov_b32_e32 v2, v0
	v_mov_b32_e32 v3, v0
	v_mov_b32_e32 v1, v0
	v_mov_b64_e32 v[4:5], v[2:3]
	v_mov_b64_e32 v[2:3], v[0:1]
	s_andn2_b64 vcc, exec, s[0:1]
	s_nop 0
	v_mfma_f32_16x16x32_bf16 v[2:5], v[2:5], v[2:5], 0
	s_cbranch_vccnz .LBB0_1156
	s_barrier
	s_branch .LBB0_1156
